# best4 + norm_unit: all 32 Q/K loads prefetched up front (one round trip) before the 8 serialized load-wait-compute groups
# baseline (speedup 1.0000x reference)
; __device__ __forceinline__ float bf_lo(unsigned w) { return __uint_as_float(w << 16); }
; __device__ __forceinline__ float bf_hi(unsigned w) { return __uint_as_float(w & 0xffff0000u); }
; __device__ __forceinline__ void norm_unit(const Ctx& c, int l, int tile) {
;     ...
;     for (int a = 0; a < 2; ++a)
; #pragma unroll
;         for (int hh = 0; hh < 2; ++hh) { const u32x4* p = (const u32x4*)((a == 0 ? Q : K) + (size_t)tok * 512 + (2 * part + hh) * 64);
;             float s0 = 0.f, s1 = 0.f;
; #pragma unroll
;             for (int j = 0; j < 8; ++j) { const u32x4 w = p[j];
;                 s0 += bf_lo(w.x) * bf_lo(w.x) + bf_hi(w.x) * bf_hi(w.x) + bf_lo(w.y) * bf_lo(w.y) + bf_hi(w.y) * bf_hi(w.y);
;                 s1 += bf_lo(w.z) * bf_lo(w.z) + bf_hi(w.z) * bf_hi(w.z) + bf_lo(w.w) * bf_lo(w.w) + bf_hi(w.w) * bf_hi(w.w); }
;             res[a * 2 + hh] = (s0 + s1) * 1.0001f + 1e-30f; }
.LBB0_314:
	v_readlane_b32 s12, v253, 0
	v_readlane_b32 s13, v253, 1
	s_load_dwordx4 s[20:23], s[12:13], 0xa8
	v_ashrrev_i32_e32 v17, 31, v16
	s_waitcnt lgkmcnt(0)
	v_lshlrev_b64 v[0:1], 10, v[16:17]
	s_mov_b64 s[12:13], 0x4000000
	s_mov_b64 s[42:43], 0x6000000
	s_waitcnt lgkmcnt(0)
	v_lshl_add_u64 v[12:13], s[22:23], 0, v[0:1]
	v_lshl_add_u64 v[14:15], v[12:13], 0, s[12:13]
	v_lshl_add_u64 v[20:21], v[14:15], 0, v[96:97]
	v_mov_b32_e32 v180, v18
	v_mov_b32_e32 v181, 0
	v_lshl_add_u64 v[174:175], v[14:15], 0, v[180:181]
	v_lshl_add_u64 v[176:177], v[12:13], 0, s[42:43]
	v_lshl_add_u64 v[178:179], v[176:177], 0, v[180:181]
	v_lshl_add_u64 v[176:177], v[176:177], 0, v[96:97]
	global_load_dwordx4 v[156:159], v[20:21], off
	global_load_dwordx4 v[156:159], v[20:21], off offset:16
	global_load_dwordx4 v[156:159], v[20:21], off offset:32
	global_load_dwordx4 v[156:159], v[20:21], off offset:48
	global_load_dwordx4 v[156:159], v[20:21], off offset:64
	global_load_dwordx4 v[156:159], v[20:21], off offset:80
	global_load_dwordx4 v[156:159], v[20:21], off offset:96
	global_load_dwordx4 v[156:159], v[20:21], off offset:112
	global_load_dwordx4 v[156:159], v[174:175], off
	global_load_dwordx4 v[156:159], v[174:175], off offset:16
	global_load_dwordx4 v[156:159], v[174:175], off offset:32
	global_load_dwordx4 v[156:159], v[174:175], off offset:48
	global_load_dwordx4 v[156:159], v[174:175], off offset:64
	global_load_dwordx4 v[156:159], v[174:175], off offset:80
	global_load_dwordx4 v[156:159], v[174:175], off offset:96
	global_load_dwordx4 v[156:159], v[174:175], off offset:112
	global_load_dwordx4 v[156:159], v[176:177], off
	global_load_dwordx4 v[156:159], v[176:177], off offset:16
	global_load_dwordx4 v[156:159], v[176:177], off offset:32
	global_load_dwordx4 v[156:159], v[176:177], off offset:48
	global_load_dwordx4 v[156:159], v[176:177], off offset:64
	global_load_dwordx4 v[156:159], v[176:177], off offset:80
	global_load_dwordx4 v[156:159], v[176:177], off offset:96
	global_load_dwordx4 v[156:159], v[176:177], off offset:112
	global_load_dwordx4 v[156:159], v[178:179], off
	global_load_dwordx4 v[156:159], v[178:179], off offset:16
	global_load_dwordx4 v[156:159], v[178:179], off offset:32
	global_load_dwordx4 v[156:159], v[178:179], off offset:48
	global_load_dwordx4 v[156:159], v[178:179], off offset:64
	global_load_dwordx4 v[156:159], v[178:179], off offset:80
	global_load_dwordx4 v[156:159], v[178:179], off offset:96
	global_load_dwordx4 v[156:159], v[178:179], off offset:112
	s_waitcnt vmcnt(0)
	global_load_dwordx4 v[0:3], v[20:21], off offset:48
	global_load_dwordx4 v[4:7], v[20:21], off offset:32
	global_load_dwordx4 v[8:11], v[20:21], off offset:16
	global_load_dwordx4 v[28:31], v[20:21], off
	v_lshl_add_u64 v[12:13], v[12:13], 0, s[42:43]
	s_waitcnt vmcnt(0)
	v_and_b32_e32 v19, 0xffff0000, v28
	v_lshlrev_b32_e32 v17, 16, v28
	v_mul_f32_e32 v19, v19, v19
	v_fmac_f32_e32 v19, v17, v17
	v_lshlrev_b32_e32 v17, 16, v29
	v_fmac_f32_e32 v19, v17, v17
	v_and_b32_e32 v17, 0xffff0000, v29
	v_and_b32_e32 v28, 0xffff0000, v30
	v_fmac_f32_e32 v19, v17, v17
	v_lshlrev_b32_e32 v17, 16, v30
	v_mul_f32_e32 v28, v28, v28
	v_fmac_f32_e32 v28, v17, v17
	v_lshlrev_b32_e32 v17, 16, v31
	v_fmac_f32_e32 v28, v17, v17
	v_and_b32_e32 v17, 0xffff0000, v31
	v_fmac_f32_e32 v28, v17, v17
	v_lshlrev_b32_e32 v17, 16, v8
	v_and_b32_e32 v8, 0xffff0000, v8
	v_mul_f32_e32 v8, v8, v8
	v_fmac_f32_e32 v8, v17, v17
	v_lshlrev_b32_e32 v17, 16, v9
	v_fmac_f32_e32 v8, v17, v17
	v_and_b32_e32 v9, 0xffff0000, v9
	v_fmac_f32_e32 v8, v9, v9
	v_lshlrev_b32_e32 v9, 16, v10
	v_and_b32_e32 v10, 0xffff0000, v10
	v_mul_f32_e32 v10, v10, v10
	v_fmac_f32_e32 v10, v9, v9
	v_lshlrev_b32_e32 v9, 16, v11
	v_fmac_f32_e32 v10, v9, v9
	v_and_b32_e32 v9, 0xffff0000, v11
	v_fmac_f32_e32 v10, v9, v9
	v_add_f32_e32 v9, v28, v10
	v_lshlrev_b32_e32 v10, 16, v4
	v_and_b32_e32 v4, 0xffff0000, v4
	v_mul_f32_e32 v4, v4, v4
	v_fmac_f32_e32 v4, v10, v10
	v_lshlrev_b32_e32 v10, 16, v5
	v_fmac_f32_e32 v4, v10, v10
	v_and_b32_e32 v5, 0xffff0000, v5
	v_fmac_f32_e32 v4, v5, v5
	v_lshlrev_b32_e32 v5, 16, v6
	v_and_b32_e32 v6, 0xffff0000, v6
	v_mul_f32_e32 v6, v6, v6
	v_fmac_f32_e32 v6, v5, v5
	v_lshlrev_b32_e32 v5, 16, v7
	v_fmac_f32_e32 v6, v5, v5
	v_and_b32_e32 v5, 0xffff0000, v7
	v_fmac_f32_e32 v6, v5, v5
	v_add_f32_e32 v5, v9, v6
	v_lshlrev_b32_e32 v6, 16, v0
	v_and_b32_e32 v0, 0xffff0000, v0
	v_mul_f32_e32 v0, v0, v0
	v_fmac_f32_e32 v0, v6, v6
	v_lshlrev_b32_e32 v6, 16, v1
	v_add_f32_e32 v8, v19, v8
	v_fmac_f32_e32 v0, v6, v6
	v_and_b32_e32 v1, 0xffff0000, v1
	v_add_f32_e32 v4, v8, v4
	v_fmac_f32_e32 v0, v1, v1
	v_and_b32_e32 v1, 0xffff0000, v2
	v_add_f32_e32 v17, v4, v0
	v_lshlrev_b32_e32 v0, 16, v2
	v_mul_f32_e32 v1, v1, v1
	v_fmac_f32_e32 v1, v0, v0
	v_lshlrev_b32_e32 v0, 16, v3
	v_fmac_f32_e32 v1, v0, v0
	v_and_b32_e32 v0, 0xffff0000, v3
	v_fmac_f32_e32 v1, v0, v0
	v_add_f32_e32 v19, v5, v1
	global_load_dwordx4 v[0:3], v[20:21], off offset:112
	global_load_dwordx4 v[4:7], v[20:21], off offset:96
	global_load_dwordx4 v[8:11], v[20:21], off offset:80
	global_load_dwordx4 v[28:31], v[20:21], off offset:64
	s_waitcnt vmcnt(0)
; __device__ __forceinline__ float bf_lo(unsigned w) { return __uint_as_float(w << 16); }
; __device__ __forceinline__ float bf_hi(unsigned w) { return __uint_as_float(w & 0xffff0000u); }
; __device__ __forceinline__ void norm_unit(const Ctx& c, int l, int tile) {
;     ...
;         for (int hh = 0; hh < 2; ++hh) { const u32x4* p = (const u32x4*)((a == 0 ? Q : K) + (size_t)tok * 512 + (2 * part + hh) * 64);
;             float s0 = 0.f, s1 = 0.f;
; #pragma unroll
;             for (int j = 0; j < 8; ++j) { const u32x4 w = p[j];
;                 s0 += bf_lo(w.x) * bf_lo(w.x) + bf_hi(w.x) * bf_hi(w.x) + bf_lo(w.y) * bf_lo(w.y) + bf_hi(w.y) * bf_hi(w.y);
;                 s1 += bf_lo(w.z) * bf_lo(w.z) + bf_hi(w.z) * bf_hi(w.z) + bf_lo(w.w) * bf_lo(w.w) + bf_hi(w.w) * bf_hi(w.w); }
;             res[a * 2 + hh] = (s0 + s1) * 1.0001f + 1e-30f; }
	v_and_b32_e32 v21, 0xffff0000, v28
	v_lshlrev_b32_e32 v20, 16, v28
	v_mul_f32_e32 v21, v21, v21
	v_fmac_f32_e32 v21, v20, v20
	v_lshlrev_b32_e32 v20, 16, v29
	v_fmac_f32_e32 v21, v20, v20
	v_and_b32_e32 v20, 0xffff0000, v29
	v_fmac_f32_e32 v21, v20, v20
	v_add_f32_e32 v17, v17, v21
	v_and_b32_e32 v21, 0xffff0000, v30
	v_lshlrev_b32_e32 v20, 16, v30
	v_mul_f32_e32 v21, v21, v21
	v_fmac_f32_e32 v21, v20, v20
	v_lshlrev_b32_e32 v20, 16, v31
	v_fmac_f32_e32 v21, v20, v20
	v_and_b32_e32 v20, 0xffff0000, v31
	v_fmac_f32_e32 v21, v20, v20
	v_lshlrev_b32_e32 v20, 16, v8
	v_and_b32_e32 v8, 0xffff0000, v8
	v_mul_f32_e32 v8, v8, v8
	v_fmac_f32_e32 v8, v20, v20
	v_lshlrev_b32_e32 v20, 16, v9
	v_fmac_f32_e32 v8, v20, v20
	v_and_b32_e32 v9, 0xffff0000, v9
	v_fmac_f32_e32 v8, v9, v9
	v_lshlrev_b32_e32 v9, 16, v10
	v_and_b32_e32 v10, 0xffff0000, v10
	v_mul_f32_e32 v10, v10, v10
	v_fmac_f32_e32 v10, v9, v9
	v_lshlrev_b32_e32 v9, 16, v11
	v_fmac_f32_e32 v10, v9, v9
	v_and_b32_e32 v9, 0xffff0000, v11
	v_add_f32_e32 v19, v19, v21
	v_fmac_f32_e32 v10, v9, v9
	v_add_f32_e32 v9, v19, v10
	v_lshlrev_b32_e32 v10, 16, v4
	v_and_b32_e32 v4, 0xffff0000, v4
	v_mul_f32_e32 v4, v4, v4
	v_fmac_f32_e32 v4, v10, v10
	v_lshlrev_b32_e32 v10, 16, v5
	v_fmac_f32_e32 v4, v10, v10
	v_and_b32_e32 v5, 0xffff0000, v5
	v_fmac_f32_e32 v4, v5, v5
	v_lshlrev_b32_e32 v5, 16, v6
	v_and_b32_e32 v6, 0xffff0000, v6
	v_mul_f32_e32 v6, v6, v6
	v_fmac_f32_e32 v6, v5, v5
	v_lshlrev_b32_e32 v5, 16, v7
	v_fmac_f32_e32 v6, v5, v5
	v_and_b32_e32 v5, 0xffff0000, v7
	v_fmac_f32_e32 v6, v5, v5
	v_add_f32_e32 v5, v9, v6
	v_lshlrev_b32_e32 v6, 16, v0
	v_and_b32_e32 v0, 0xffff0000, v0
	v_mul_f32_e32 v0, v0, v0
	v_fmac_f32_e32 v0, v6, v6
	v_lshlrev_b32_e32 v6, 16, v1
	v_fmac_f32_e32 v0, v6, v6
	v_and_b32_e32 v1, 0xffff0000, v1
	v_fmac_f32_e32 v0, v1, v1
	v_lshlrev_b32_e32 v1, 16, v2
	v_and_b32_e32 v2, 0xffff0000, v2
	v_mul_f32_e32 v2, v2, v2
	v_fmac_f32_e32 v2, v1, v1
	v_lshlrev_b32_e32 v1, 16, v3
	v_add_f32_e32 v8, v17, v8
	v_fmac_f32_e32 v2, v1, v1
	v_and_b32_e32 v1, 0xffff0000, v3
	v_add_f32_e32 v4, v8, v4
	v_fmac_f32_e32 v2, v1, v1
	v_add_f32_e32 v0, v4, v0
	v_add_f32_e32 v1, v5, v2
	v_mov_b32_e32 v19, v97
	v_add_f32_e32 v0, v0, v1
	v_lshl_add_u64 v[14:15], v[14:15], 0, v[18:19]
	v_fmamk_f32 v17, v0, 0x3f800347, v217
	global_load_dwordx4 v[0:3], v[14:15], off offset:48
	global_load_dwordx4 v[4:7], v[14:15], off offset:32
	global_load_dwordx4 v[8:11], v[14:15], off offset:16
	global_load_dwordx4 v[28:31], v[14:15], off
	s_waitcnt vmcnt(0)
	v_and_b32_e32 v21, 0xffff0000, v28
	v_lshlrev_b32_e32 v20, 16, v28
	v_mul_f32_e32 v21, v21, v21
	v_fmac_f32_e32 v21, v20, v20
	v_lshlrev_b32_e32 v20, 16, v29
	v_fmac_f32_e32 v21, v20, v20
	v_and_b32_e32 v20, 0xffff0000, v29
	v_and_b32_e32 v28, 0xffff0000, v30
	v_fmac_f32_e32 v21, v20, v20
	v_lshlrev_b32_e32 v20, 16, v30
	v_mul_f32_e32 v28, v28, v28
	v_fmac_f32_e32 v28, v20, v20
	v_lshlrev_b32_e32 v20, 16, v31
	v_fmac_f32_e32 v28, v20, v20
	v_and_b32_e32 v20, 0xffff0000, v31
	v_fmac_f32_e32 v28, v20, v20
	v_lshlrev_b32_e32 v20, 16, v8
	v_and_b32_e32 v8, 0xffff0000, v8
	v_mul_f32_e32 v8, v8, v8
	v_fmac_f32_e32 v8, v20, v20
	v_lshlrev_b32_e32 v20, 16, v9
	v_fmac_f32_e32 v8, v20, v20
	v_and_b32_e32 v9, 0xffff0000, v9
	v_fmac_f32_e32 v8, v9, v9
	v_lshlrev_b32_e32 v9, 16, v10
	v_and_b32_e32 v10, 0xffff0000, v10
	v_mul_f32_e32 v10, v10, v10
	v_fmac_f32_e32 v10, v9, v9
	v_lshlrev_b32_e32 v9, 16, v11
	v_fmac_f32_e32 v10, v9, v9
	v_and_b32_e32 v9, 0xffff0000, v11
	v_fmac_f32_e32 v10, v9, v9
	v_add_f32_e32 v9, v28, v10
	v_lshlrev_b32_e32 v10, 16, v4
	v_and_b32_e32 v4, 0xffff0000, v4
	v_mul_f32_e32 v4, v4, v4
	v_fmac_f32_e32 v4, v10, v10
	v_lshlrev_b32_e32 v10, 16, v5
	v_fmac_f32_e32 v4, v10, v10
	v_and_b32_e32 v5, 0xffff0000, v5
	v_fmac_f32_e32 v4, v5, v5
	v_lshlrev_b32_e32 v5, 16, v6
	v_and_b32_e32 v6, 0xffff0000, v6
	v_mul_f32_e32 v6, v6, v6
	v_fmac_f32_e32 v6, v5, v5
	v_lshlrev_b32_e32 v5, 16, v7
	v_fmac_f32_e32 v6, v5, v5
	v_and_b32_e32 v5, 0xffff0000, v7
	v_fmac_f32_e32 v6, v5, v5
	v_add_f32_e32 v5, v9, v6
	v_lshlrev_b32_e32 v6, 16, v0
	v_and_b32_e32 v0, 0xffff0000, v0
	v_mul_f32_e32 v0, v0, v0
	v_fmac_f32_e32 v0, v6, v6
	v_lshlrev_b32_e32 v6, 16, v1
	v_add_f32_e32 v8, v21, v8
	v_fmac_f32_e32 v0, v6, v6
	v_and_b32_e32 v1, 0xffff0000, v1
	v_add_f32_e32 v4, v8, v4
	v_fmac_f32_e32 v0, v1, v1
	v_and_b32_e32 v1, 0xffff0000, v2
	v_add_f32_e32 v20, v4, v0
	v_lshlrev_b32_e32 v0, 16, v2
	v_mul_f32_e32 v1, v1, v1
	v_fmac_f32_e32 v1, v0, v0
	v_lshlrev_b32_e32 v0, 16, v3
	v_fmac_f32_e32 v1, v0, v0
	v_and_b32_e32 v0, 0xffff0000, v3
	v_fmac_f32_e32 v1, v0, v0
	v_add_f32_e32 v21, v5, v1
	global_load_dwordx4 v[0:3], v[14:15], off offset:112
	global_load_dwordx4 v[4:7], v[14:15], off offset:96
	global_load_dwordx4 v[8:11], v[14:15], off offset:80
	global_load_dwordx4 v[28:31], v[14:15], off offset:64
	s_waitcnt vmcnt(0)
; __device__ __forceinline__ float bf_lo(unsigned w) { return __uint_as_float(w << 16); }
; __device__ __forceinline__ float bf_hi(unsigned w) { return __uint_as_float(w & 0xffff0000u); }
; __device__ __forceinline__ void norm_unit(const Ctx& c, int l, int tile) {
;     ...
;         for (int hh = 0; hh < 2; ++hh) { const u32x4* p = (const u32x4*)((a == 0 ? Q : K) + (size_t)tok * 512 + (2 * part + hh) * 64);
;             float s0 = 0.f, s1 = 0.f;
; #pragma unroll
;             for (int j = 0; j < 8; ++j) { const u32x4 w = p[j];
;                 s0 += bf_lo(w.x) * bf_lo(w.x) + bf_hi(w.x) * bf_hi(w.x) + bf_lo(w.y) * bf_lo(w.y) + bf_hi(w.y) * bf_hi(w.y);
;                 s1 += bf_lo(w.z) * bf_lo(w.z) + bf_hi(w.z) * bf_hi(w.z) + bf_lo(w.w) * bf_lo(w.w) + bf_hi(w.w) * bf_hi(w.w); }
;             res[a * 2 + hh] = (s0 + s1) * 1.0001f + 1e-30f; }
	v_and_b32_e32 v15, 0xffff0000, v28
	v_lshlrev_b32_e32 v14, 16, v28
	v_mul_f32_e32 v15, v15, v15
	v_fmac_f32_e32 v15, v14, v14
	v_lshlrev_b32_e32 v14, 16, v29
	v_fmac_f32_e32 v15, v14, v14
	v_and_b32_e32 v14, 0xffff0000, v29
	v_fmac_f32_e32 v15, v14, v14
	v_add_f32_e32 v14, v20, v15
	v_and_b32_e32 v20, 0xffff0000, v30
	v_lshlrev_b32_e32 v15, 16, v30
	v_mul_f32_e32 v20, v20, v20
	v_fmac_f32_e32 v20, v15, v15
	v_lshlrev_b32_e32 v15, 16, v31
	v_fmac_f32_e32 v20, v15, v15
	v_and_b32_e32 v15, 0xffff0000, v31
	v_fmac_f32_e32 v20, v15, v15
	v_add_f32_e32 v15, v21, v20
	v_lshlrev_b32_e32 v20, 16, v8
	v_and_b32_e32 v8, 0xffff0000, v8
	v_mul_f32_e32 v8, v8, v8
	v_fmac_f32_e32 v8, v20, v20
	v_lshlrev_b32_e32 v20, 16, v9
	v_fmac_f32_e32 v8, v20, v20
	v_and_b32_e32 v9, 0xffff0000, v9
	v_fmac_f32_e32 v8, v9, v9
	v_lshlrev_b32_e32 v9, 16, v10
	v_and_b32_e32 v10, 0xffff0000, v10
	v_mul_f32_e32 v10, v10, v10
	v_fmac_f32_e32 v10, v9, v9
	v_lshlrev_b32_e32 v9, 16, v11
	v_fmac_f32_e32 v10, v9, v9
	v_and_b32_e32 v9, 0xffff0000, v11
	v_fmac_f32_e32 v10, v9, v9
	v_add_f32_e32 v9, v15, v10
	v_lshlrev_b32_e32 v10, 16, v4
	v_and_b32_e32 v4, 0xffff0000, v4
	v_mul_f32_e32 v4, v4, v4
	v_fmac_f32_e32 v4, v10, v10
	v_lshlrev_b32_e32 v10, 16, v5
	v_fmac_f32_e32 v4, v10, v10
	v_and_b32_e32 v5, 0xffff0000, v5
	v_fmac_f32_e32 v4, v5, v5
	v_lshlrev_b32_e32 v5, 16, v6
	v_and_b32_e32 v6, 0xffff0000, v6
	v_mul_f32_e32 v6, v6, v6
	v_fmac_f32_e32 v6, v5, v5
	v_lshlrev_b32_e32 v5, 16, v7
	v_fmac_f32_e32 v6, v5, v5
	v_and_b32_e32 v5, 0xffff0000, v7
	v_fmac_f32_e32 v6, v5, v5
	v_add_f32_e32 v5, v9, v6
	v_lshlrev_b32_e32 v6, 16, v0
	v_and_b32_e32 v0, 0xffff0000, v0
	v_mul_f32_e32 v0, v0, v0
	v_fmac_f32_e32 v0, v6, v6
	v_lshlrev_b32_e32 v6, 16, v1
	v_fmac_f32_e32 v0, v6, v6
	v_and_b32_e32 v1, 0xffff0000, v1
	v_fmac_f32_e32 v0, v1, v1
	v_lshlrev_b32_e32 v1, 16, v2
	v_and_b32_e32 v2, 0xffff0000, v2
	v_mul_f32_e32 v2, v2, v2
	v_fmac_f32_e32 v2, v1, v1
	v_lshlrev_b32_e32 v1, 16, v3
	v_add_f32_e32 v8, v14, v8
	v_fmac_f32_e32 v2, v1, v1
	v_and_b32_e32 v1, 0xffff0000, v3
	v_add_f32_e32 v4, v8, v4
	v_fmac_f32_e32 v2, v1, v1
	v_add_f32_e32 v0, v4, v0
	v_add_f32_e32 v1, v5, v2
	v_add_f32_e32 v0, v0, v1
	v_lshl_add_u64 v[14:15], v[12:13], 0, v[96:97]
	v_fmamk_f32 v20, v0, 0x3f800347, v217
	global_load_dwordx4 v[0:3], v[14:15], off offset:48
	global_load_dwordx4 v[4:7], v[14:15], off offset:32
	global_load_dwordx4 v[8:11], v[14:15], off offset:16
	global_load_dwordx4 v[28:31], v[14:15], off
	v_lshl_add_u64 v[12:13], v[12:13], 0, v[18:19]
	s_waitcnt vmcnt(0)
	v_lshlrev_b32_e32 v21, 16, v28
	v_and_b32_e32 v28, 0xffff0000, v28
	v_mul_f32_e32 v28, v28, v28
	v_fmac_f32_e32 v28, v21, v21
	v_lshlrev_b32_e32 v21, 16, v29
	v_fmac_f32_e32 v28, v21, v21
	v_and_b32_e32 v21, 0xffff0000, v29
	v_and_b32_e32 v29, 0xffff0000, v30
	v_fmac_f32_e32 v28, v21, v21
	v_lshlrev_b32_e32 v21, 16, v30
	v_mul_f32_e32 v29, v29, v29
	v_fmac_f32_e32 v29, v21, v21
	v_lshlrev_b32_e32 v21, 16, v31
	v_fmac_f32_e32 v29, v21, v21
	v_and_b32_e32 v21, 0xffff0000, v31
	v_fmac_f32_e32 v29, v21, v21
	v_lshlrev_b32_e32 v21, 16, v8
	v_and_b32_e32 v8, 0xffff0000, v8
	v_mul_f32_e32 v8, v8, v8
	v_fmac_f32_e32 v8, v21, v21
	v_lshlrev_b32_e32 v21, 16, v9
	v_fmac_f32_e32 v8, v21, v21
	v_and_b32_e32 v9, 0xffff0000, v9
	v_fmac_f32_e32 v8, v9, v9
	v_lshlrev_b32_e32 v9, 16, v10
	v_and_b32_e32 v10, 0xffff0000, v10
	v_mul_f32_e32 v10, v10, v10
	v_fmac_f32_e32 v10, v9, v9
	v_lshlrev_b32_e32 v9, 16, v11
	v_fmac_f32_e32 v10, v9, v9
	v_and_b32_e32 v9, 0xffff0000, v11
	v_fmac_f32_e32 v10, v9, v9
	v_add_f32_e32 v9, v29, v10
	v_lshlrev_b32_e32 v10, 16, v4
	v_and_b32_e32 v4, 0xffff0000, v4
	v_mul_f32_e32 v4, v4, v4
	v_fmac_f32_e32 v4, v10, v10
	v_lshlrev_b32_e32 v10, 16, v5
	v_fmac_f32_e32 v4, v10, v10
	v_and_b32_e32 v5, 0xffff0000, v5
	v_fmac_f32_e32 v4, v5, v5
	v_lshlrev_b32_e32 v5, 16, v6
	v_and_b32_e32 v6, 0xffff0000, v6
	v_mul_f32_e32 v6, v6, v6
	v_fmac_f32_e32 v6, v5, v5
	v_lshlrev_b32_e32 v5, 16, v7
	v_fmac_f32_e32 v6, v5, v5
	v_and_b32_e32 v5, 0xffff0000, v7
	v_fmac_f32_e32 v6, v5, v5
	v_add_f32_e32 v5, v9, v6
	v_lshlrev_b32_e32 v6, 16, v0
	v_and_b32_e32 v0, 0xffff0000, v0
	v_mul_f32_e32 v0, v0, v0
	v_fmac_f32_e32 v0, v6, v6
	v_lshlrev_b32_e32 v6, 16, v1
	v_add_f32_e32 v8, v28, v8
	v_fmac_f32_e32 v0, v6, v6
	v_and_b32_e32 v1, 0xffff0000, v1
	v_add_f32_e32 v4, v8, v4
	v_fmac_f32_e32 v0, v1, v1
	v_and_b32_e32 v1, 0xffff0000, v2
	v_add_f32_e32 v21, v4, v0
	v_lshlrev_b32_e32 v0, 16, v2
	v_mul_f32_e32 v1, v1, v1
	v_fmac_f32_e32 v1, v0, v0
	v_lshlrev_b32_e32 v0, 16, v3
	v_fmac_f32_e32 v1, v0, v0
	v_and_b32_e32 v0, 0xffff0000, v3
	v_fmac_f32_e32 v1, v0, v0
	v_add_f32_e32 v28, v5, v1
	global_load_dwordx4 v[0:3], v[14:15], off offset:112
	global_load_dwordx4 v[4:7], v[14:15], off offset:96
	global_load_dwordx4 v[8:11], v[14:15], off offset:80
	global_load_dwordx4 v[30:33], v[14:15], off offset:64
	s_waitcnt vmcnt(0)
; __device__ __forceinline__ float bf_lo(unsigned w) { return __uint_as_float(w << 16); }
; __device__ __forceinline__ float bf_hi(unsigned w) { return __uint_as_float(w & 0xffff0000u); }
; __device__ __forceinline__ void norm_unit(const Ctx& c, int l, int tile) {
;     ...
;         for (int hh = 0; hh < 2; ++hh) { const u32x4* p = (const u32x4*)((a == 0 ? Q : K) + (size_t)tok * 512 + (2 * part + hh) * 64);
;             float s0 = 0.f, s1 = 0.f;
; #pragma unroll
;             for (int j = 0; j < 8; ++j) { const u32x4 w = p[j];
;                 s0 += bf_lo(w.x) * bf_lo(w.x) + bf_hi(w.x) * bf_hi(w.x) + bf_lo(w.y) * bf_lo(w.y) + bf_hi(w.y) * bf_hi(w.y);
;                 s1 += bf_lo(w.z) * bf_lo(w.z) + bf_hi(w.z) * bf_hi(w.z) + bf_lo(w.w) * bf_lo(w.w) + bf_hi(w.w) * bf_hi(w.w); }
;             res[a * 2 + hh] = (s0 + s1) * 1.0001f + 1e-30f; }
	v_and_b32_e32 v15, 0xffff0000, v30
	v_lshlrev_b32_e32 v14, 16, v30
	v_mul_f32_e32 v15, v15, v15
	v_fmac_f32_e32 v15, v14, v14
	v_lshlrev_b32_e32 v14, 16, v31
	v_fmac_f32_e32 v15, v14, v14
	v_and_b32_e32 v14, 0xffff0000, v31
	v_fmac_f32_e32 v15, v14, v14
	v_add_f32_e32 v14, v21, v15
	v_and_b32_e32 v21, 0xffff0000, v32
	v_lshlrev_b32_e32 v15, 16, v32
	v_mul_f32_e32 v21, v21, v21
	v_fmac_f32_e32 v21, v15, v15
	v_lshlrev_b32_e32 v15, 16, v33
	v_fmac_f32_e32 v21, v15, v15
	v_and_b32_e32 v15, 0xffff0000, v33
	v_fmac_f32_e32 v21, v15, v15
	v_add_f32_e32 v15, v28, v21
	v_lshlrev_b32_e32 v21, 16, v8
	v_and_b32_e32 v8, 0xffff0000, v8
	v_mul_f32_e32 v8, v8, v8
	v_fmac_f32_e32 v8, v21, v21
	v_lshlrev_b32_e32 v21, 16, v9
	v_fmac_f32_e32 v8, v21, v21
	v_and_b32_e32 v9, 0xffff0000, v9
	v_fmac_f32_e32 v8, v9, v9
	v_lshlrev_b32_e32 v9, 16, v10
	v_and_b32_e32 v10, 0xffff0000, v10
	v_mul_f32_e32 v10, v10, v10
	v_fmac_f32_e32 v10, v9, v9
	v_lshlrev_b32_e32 v9, 16, v11
	v_fmac_f32_e32 v10, v9, v9
	v_and_b32_e32 v9, 0xffff0000, v11
	v_fmac_f32_e32 v10, v9, v9
	v_add_f32_e32 v9, v15, v10
	v_lshlrev_b32_e32 v10, 16, v4
	v_and_b32_e32 v4, 0xffff0000, v4
	v_mul_f32_e32 v4, v4, v4
	v_fmac_f32_e32 v4, v10, v10
	v_lshlrev_b32_e32 v10, 16, v5
	v_fmac_f32_e32 v4, v10, v10
	v_and_b32_e32 v5, 0xffff0000, v5
	v_fmac_f32_e32 v4, v5, v5
	v_lshlrev_b32_e32 v5, 16, v6
	v_and_b32_e32 v6, 0xffff0000, v6
	v_mul_f32_e32 v6, v6, v6
	v_fmac_f32_e32 v6, v5, v5
	v_lshlrev_b32_e32 v5, 16, v7
	v_fmac_f32_e32 v6, v5, v5
	v_and_b32_e32 v5, 0xffff0000, v7
	v_fmac_f32_e32 v6, v5, v5
	v_add_f32_e32 v5, v9, v6
	v_lshlrev_b32_e32 v6, 16, v0
	v_and_b32_e32 v0, 0xffff0000, v0
	v_mul_f32_e32 v0, v0, v0
	v_fmac_f32_e32 v0, v6, v6
	v_lshlrev_b32_e32 v6, 16, v1
	v_fmac_f32_e32 v0, v6, v6
	v_and_b32_e32 v1, 0xffff0000, v1
	v_fmac_f32_e32 v0, v1, v1
	v_lshlrev_b32_e32 v1, 16, v2
	v_and_b32_e32 v2, 0xffff0000, v2
	v_mul_f32_e32 v2, v2, v2
	v_fmac_f32_e32 v2, v1, v1
	v_lshlrev_b32_e32 v1, 16, v3
	v_add_f32_e32 v8, v14, v8
	v_fmac_f32_e32 v2, v1, v1
	v_and_b32_e32 v1, 0xffff0000, v3
	v_add_f32_e32 v4, v8, v4
	v_fmac_f32_e32 v2, v1, v1
	v_add_f32_e32 v0, v4, v0
	v_add_f32_e32 v1, v5, v2
	v_add_f32_e32 v0, v0, v1
	v_fmamk_f32 v21, v0, 0x3f800347, v217
	global_load_dwordx4 v[0:3], v[12:13], off offset:48
	global_load_dwordx4 v[4:7], v[12:13], off offset:32
	global_load_dwordx4 v[8:11], v[12:13], off offset:16
	global_load_dwordx4 v[28:31], v[12:13], off
	s_waitcnt vmcnt(0)
	v_and_b32_e32 v15, 0xffff0000, v28
	v_lshlrev_b32_e32 v14, 16, v28
	v_mul_f32_e32 v15, v15, v15
	v_fmac_f32_e32 v15, v14, v14
	v_lshlrev_b32_e32 v14, 16, v29
	v_fmac_f32_e32 v15, v14, v14
	v_and_b32_e32 v14, 0xffff0000, v29
	v_and_b32_e32 v19, 0xffff0000, v30
	v_fmac_f32_e32 v15, v14, v14
	v_lshlrev_b32_e32 v14, 16, v30
	v_mul_f32_e32 v19, v19, v19
	v_fmac_f32_e32 v19, v14, v14
	v_lshlrev_b32_e32 v14, 16, v31
	v_fmac_f32_e32 v19, v14, v14
	v_and_b32_e32 v14, 0xffff0000, v31
	v_fmac_f32_e32 v19, v14, v14
	v_lshlrev_b32_e32 v14, 16, v8
	v_and_b32_e32 v8, 0xffff0000, v8
	v_mul_f32_e32 v8, v8, v8
	v_fmac_f32_e32 v8, v14, v14
	v_lshlrev_b32_e32 v14, 16, v9
	v_fmac_f32_e32 v8, v14, v14
	v_and_b32_e32 v9, 0xffff0000, v9
	v_fmac_f32_e32 v8, v9, v9
	v_lshlrev_b32_e32 v9, 16, v10
	v_and_b32_e32 v10, 0xffff0000, v10
	v_mul_f32_e32 v10, v10, v10
	v_fmac_f32_e32 v10, v9, v9
	v_lshlrev_b32_e32 v9, 16, v11
	v_fmac_f32_e32 v10, v9, v9
	v_and_b32_e32 v9, 0xffff0000, v11
	v_fmac_f32_e32 v10, v9, v9
	v_add_f32_e32 v9, v19, v10
	v_lshlrev_b32_e32 v10, 16, v4
	v_and_b32_e32 v4, 0xffff0000, v4
	v_mul_f32_e32 v4, v4, v4
	v_fmac_f32_e32 v4, v10, v10
	v_lshlrev_b32_e32 v10, 16, v5
	v_fmac_f32_e32 v4, v10, v10
	v_and_b32_e32 v5, 0xffff0000, v5
	v_fmac_f32_e32 v4, v5, v5
	v_lshlrev_b32_e32 v5, 16, v6
	v_and_b32_e32 v6, 0xffff0000, v6
	v_mul_f32_e32 v6, v6, v6
	v_fmac_f32_e32 v6, v5, v5
	v_lshlrev_b32_e32 v5, 16, v7
	v_fmac_f32_e32 v6, v5, v5
	v_and_b32_e32 v5, 0xffff0000, v7
	v_fmac_f32_e32 v6, v5, v5
	v_add_f32_e32 v5, v9, v6
	v_lshlrev_b32_e32 v6, 16, v0
	v_and_b32_e32 v0, 0xffff0000, v0
	v_mul_f32_e32 v0, v0, v0
	v_fmac_f32_e32 v0, v6, v6
	v_lshlrev_b32_e32 v6, 16, v1
	v_add_f32_e32 v8, v15, v8
	v_fmac_f32_e32 v0, v6, v6
	v_and_b32_e32 v1, 0xffff0000, v1
	v_add_f32_e32 v4, v8, v4
	v_fmac_f32_e32 v0, v1, v1
	v_and_b32_e32 v1, 0xffff0000, v2
	v_add_f32_e32 v28, v4, v0
	v_lshlrev_b32_e32 v0, 16, v2
	v_mul_f32_e32 v1, v1, v1
	v_fmac_f32_e32 v1, v0, v0
	v_lshlrev_b32_e32 v0, 16, v3
	v_fmac_f32_e32 v1, v0, v0
	v_and_b32_e32 v0, 0xffff0000, v3
	v_fmac_f32_e32 v1, v0, v0
	v_add_f32_e32 v19, v5, v1
	global_load_dwordx4 v[0:3], v[12:13], off offset:112
	global_load_dwordx4 v[4:7], v[12:13], off offset:96
	global_load_dwordx4 v[8:11], v[12:13], off offset:80
	s_nop 0
	global_load_dwordx4 v[12:15], v[12:13], off offset:64
	s_waitcnt vmcnt(0)
; __device__ __forceinline__ float bf_lo(unsigned w) { return __uint_as_float(w << 16); }
; __device__ __forceinline__ float bf_hi(unsigned w) { return __uint_as_float(w & 0xffff0000u); }
; __device__ __forceinline__ void norm_unit(const Ctx& c, int l, int tile) {
;     ...
;             for (int j = 0; j < 8; ++j) { const u32x4 w = p[j];
;                 s0 += bf_lo(w.x) * bf_lo(w.x) + bf_hi(w.x) * bf_hi(w.x) + bf_lo(w.y) * bf_lo(w.y) + bf_hi(w.y) * bf_hi(w.y);
;                 s1 += bf_lo(w.z) * bf_lo(w.z) + bf_hi(w.z) * bf_hi(w.z) + bf_lo(w.w) * bf_lo(w.w) + bf_hi(w.w) * bf_hi(w.w); }
;             res[a * 2 + hh] = (s0 + s1) * 1.0001f + 1e-30f; }
; #pragma unroll
;     for (int i = 0; i < 4; ++i) { float v = res[i];
; #pragma unroll
;         for (int o = 4; o < 64; o <<= 1) v = fmaxf(v, __shfl_xor(v, o));
;         res[i] = v; }
;     if (c.lane < 4) {
; #pragma unroll
;         for (int a = 0; a < 2; ++a)
; #pragma unroll
;             for (int hh = 0; hh < 2; ++hh) atomicMax(nrm + (size_t)(b * 8 + 2 * part + hh) * 2 + a, __float_as_uint(res[a * 2 + hh]));
;     }
	v_lshlrev_b32_e32 v29, 16, v12
	v_and_b32_e32 v12, 0xffff0000, v12
	v_mul_f32_e32 v12, v12, v12
	v_fmac_f32_e32 v12, v29, v29
	v_lshlrev_b32_e32 v29, 16, v13
	v_fmac_f32_e32 v12, v29, v29
	v_and_b32_e32 v13, 0xffff0000, v13
	v_fmac_f32_e32 v12, v13, v13
	v_lshlrev_b32_e32 v13, 16, v14
	v_and_b32_e32 v14, 0xffff0000, v14
	v_mul_f32_e32 v14, v14, v14
	v_fmac_f32_e32 v14, v13, v13
	v_lshlrev_b32_e32 v13, 16, v15
	v_fmac_f32_e32 v14, v13, v13
	v_and_b32_e32 v13, 0xffff0000, v15
	v_fmac_f32_e32 v14, v13, v13
	v_add_f32_e32 v13, v19, v14
	v_lshlrev_b32_e32 v14, 16, v8
	v_and_b32_e32 v8, 0xffff0000, v8
	v_mul_f32_e32 v8, v8, v8
	v_fmac_f32_e32 v8, v14, v14
	v_lshlrev_b32_e32 v14, 16, v9
	v_fmac_f32_e32 v8, v14, v14
	v_and_b32_e32 v9, 0xffff0000, v9
	v_fmac_f32_e32 v8, v9, v9
	v_lshlrev_b32_e32 v9, 16, v10
	v_and_b32_e32 v10, 0xffff0000, v10
	v_mul_f32_e32 v10, v10, v10
	v_fmac_f32_e32 v10, v9, v9
	v_lshlrev_b32_e32 v9, 16, v11
	v_fmac_f32_e32 v10, v9, v9
	v_and_b32_e32 v9, 0xffff0000, v11
	v_fmac_f32_e32 v10, v9, v9
	v_add_f32_e32 v9, v13, v10
	v_lshlrev_b32_e32 v10, 16, v4
	v_and_b32_e32 v4, 0xffff0000, v4
	v_mul_f32_e32 v4, v4, v4
	v_fmac_f32_e32 v4, v10, v10
	v_lshlrev_b32_e32 v10, 16, v5
	v_fmac_f32_e32 v4, v10, v10
	v_and_b32_e32 v5, 0xffff0000, v5
	v_fmac_f32_e32 v4, v5, v5
	v_lshlrev_b32_e32 v5, 16, v6
	v_and_b32_e32 v6, 0xffff0000, v6
	v_mul_f32_e32 v6, v6, v6
	v_fmac_f32_e32 v6, v5, v5
	v_lshlrev_b32_e32 v5, 16, v7
	v_fmac_f32_e32 v6, v5, v5
	v_and_b32_e32 v5, 0xffff0000, v7
	v_fmac_f32_e32 v6, v5, v5
	v_add_f32_e32 v5, v9, v6
	v_lshlrev_b32_e32 v6, 16, v0
	v_and_b32_e32 v0, 0xffff0000, v0
	v_mul_f32_e32 v0, v0, v0
	v_fmac_f32_e32 v0, v6, v6
	v_lshlrev_b32_e32 v6, 16, v1
	v_fmac_f32_e32 v0, v6, v6
	v_and_b32_e32 v1, 0xffff0000, v1
	v_fmac_f32_e32 v0, v1, v1
	v_lshlrev_b32_e32 v1, 16, v2
	v_and_b32_e32 v2, 0xffff0000, v2
	v_mul_f32_e32 v2, v2, v2
	v_add_f32_e32 v12, v28, v12
	v_fmac_f32_e32 v2, v1, v1
	v_lshlrev_b32_e32 v1, 16, v3
	v_add_f32_e32 v8, v12, v8
	v_fmac_f32_e32 v2, v1, v1
	v_and_b32_e32 v1, 0xffff0000, v3
	v_add_f32_e32 v4, v8, v4
	v_fmac_f32_e32 v2, v1, v1
	v_add_f32_e32 v0, v4, v0
	v_add_f32_e32 v1, v5, v2
	v_add_f32_e32 v0, v0, v1
	v_fmamk_f32 v6, v0, 0x3f800347, v217
	ds_bpermute_b32 v0, v22, v17
	ds_bpermute_b32 v2, v22, v20
	ds_bpermute_b32 v4, v22, v21
	ds_bpermute_b32 v7, v22, v6
	s_waitcnt lgkmcnt(3)
	v_max_f32_e32 v0, v0, v0
	s_waitcnt lgkmcnt(2)
	v_max_f32_e32 v2, v2, v2
	s_waitcnt lgkmcnt(1)
	v_max_f32_e32 v4, v4, v4
	s_waitcnt lgkmcnt(0)
	v_max_f32_e32 v7, v7, v7
	v_max_f32_e32 v0, v17, v0
	v_max_f32_e32 v2, v20, v2
	v_max_f32_e32 v4, v21, v4
	v_max_f32_e32 v6, v6, v7
	ds_bpermute_b32 v1, v23, v0
	ds_bpermute_b32 v3, v23, v2
	ds_bpermute_b32 v5, v23, v4
	ds_bpermute_b32 v7, v23, v6
	s_waitcnt lgkmcnt(3)
	v_max_f32_e32 v1, v1, v1
	s_waitcnt lgkmcnt(2)
	v_max_f32_e32 v3, v3, v3
	s_waitcnt lgkmcnt(1)
	v_max_f32_e32 v5, v5, v5
	s_waitcnt lgkmcnt(0)
	v_max_f32_e32 v7, v7, v7
	v_max_f32_e32 v0, v0, v1
	v_max_f32_e32 v2, v2, v3
	v_max_f32_e32 v4, v4, v5
	v_max_f32_e32 v6, v6, v7
	ds_bpermute_b32 v1, v24, v0
	ds_bpermute_b32 v3, v24, v2
	ds_bpermute_b32 v5, v24, v4
	ds_bpermute_b32 v7, v24, v6
	s_waitcnt lgkmcnt(3)
	v_max_f32_e32 v1, v1, v1
	s_waitcnt lgkmcnt(2)
	v_max_f32_e32 v3, v3, v3
	s_waitcnt lgkmcnt(1)
	v_max_f32_e32 v5, v5, v5
	s_waitcnt lgkmcnt(0)
	v_max_f32_e32 v7, v7, v7
	v_max_f32_e32 v0, v0, v1
	v_max_f32_e32 v2, v2, v3
	v_max_f32_e32 v4, v4, v5
	v_max_f32_e32 v6, v6, v7
	ds_bpermute_b32 v1, v25, v0
	ds_bpermute_b32 v3, v25, v2
	ds_bpermute_b32 v5, v25, v4
	ds_bpermute_b32 v7, v25, v6
	s_and_saveexec_b64 s[42:43], s[38:39]
	s_cbranch_execz .LBB0_313
	s_waitcnt lgkmcnt(0)
	v_max_f32_e32 v7, v7, v7
	v_max_f32_e32 v6, v6, v6
	v_max_f32_e32 v1, v1, v1
	v_max_f32_e32 v0, v0, v0
	v_max_f32_e32 v6, v6, v7
	v_max_f32_e32 v7, v0, v1
	v_max_f32_e32 v0, v3, v3
	v_max_f32_e32 v1, v2, v2
	v_max_f32_e32 v8, v1, v0
	v_max_f32_e32 v0, v5, v5
	v_max_f32_e32 v1, v4, v4
	s_ashr_i32 s6, s0, 2
	v_max_f32_e32 v4, v1, v0
	v_and_or_b32 v0, s6, -8, v27
	v_ashrrev_i32_e32 v1, 31, v0
	v_lshl_add_u64 v[2:3], v[0:1], 3, s[40:41]
	v_or_b32_e32 v0, 1, v0
	v_ashrrev_i32_e32 v1, 31, v0
	global_atomic_umax v[2:3], v7, off
	v_lshl_add_u64 v[0:1], v[0:1], 3, s[40:41]
	global_atomic_umax v[0:1], v8, off
	global_atomic_umax v[2:3], v4, off offset:4
	global_atomic_umax v[0:1], v6, off offset:4
	s_branch .LBB0_313
